# RoPE epilogue: cos/sin loads of all seven row groups issued together at the epilogue start into separate registers, single wait, no per-group waits behind earlier stores
# baseline (speedup 1.0000x reference)
.LBB0_465:
	ds_read_b128 v[2:5], v175
	ds_read_b128 v[6:9], v176
	ds_read_b128 v[10:13], v177
	ds_read_b128 v[14:17], v178
	s_add_u32 s34, s30, 0xfffc0080
	s_addc_u32 s35, s31, -1
	s_cmp_eq_u32 s68, 12
	s_cselect_b32 s37, s9, s35
	s_cselect_b32 s36, s11, s34
	s_cselect_b32 s35, s23, s67
	s_cselect_b32 s34, s25, s66
	v_lshl_add_u64 v[164:165], s[30:31], 0, v[156:157]
	s_add_i32 m0, s45, 0xc000
	ds_read_b128 v[194:197], v191
	ds_read_b128 v[198:201], v191 offset:1024
	ds_read_b128 v[202:205], v191 offset:2048
	ds_read_b128 v[206:209], v191 offset:3072
	ds_read_b128 v[216:219], v191 offset:4096
	ds_read_b128 v[220:223], v191 offset:5120
	ds_read_b128 v[224:227], v191 offset:6144
	ds_read_b128 v[228:231], v191 offset:7168
	global_load_lds_dwordx4 v[164:165], off
	v_lshl_add_u64 v[164:165], s[30:31], 0, v[158:159]
	s_add_i32 m0, s45, 0xe000
	s_nop 0
	global_load_lds_dwordx4 v[164:165], off
	s_waitcnt lgkmcnt(8)
	s_barrier
	s_waitcnt lgkmcnt(0)
	s_setprio 1
	s_waitcnt lgkmcnt(0)
	v_mfma_scale_f32_16x16x128_f8f6f4 v[142:145], v[2:9], v[194:201], v[142:145], v192, v192 op_sel_hi:[0,0,0]
	v_mfma_scale_f32_16x16x128_f8f6f4 v[138:141], v[10:17], v[194:201], v[138:141], v192, v192 op_sel_hi:[0,0,0]
	v_mfma_scale_f32_16x16x128_f8f6f4 v[126:129], v[2:9], v[202:209], v[126:129], v192, v192 op_sel_hi:[0,0,0]
	v_mfma_scale_f32_16x16x128_f8f6f4 v[122:125], v[10:17], v[202:209], v[122:125], v192, v192 op_sel_hi:[0,0,0]
	v_mfma_scale_f32_16x16x128_f8f6f4 v[110:113], v[2:9], v[216:223], v[110:113], v192, v192 op_sel_hi:[0,0,0]
	v_mfma_scale_f32_16x16x128_f8f6f4 v[106:109], v[10:17], v[216:223], v[106:109], v192, v192 op_sel_hi:[0,0,0]
	v_mfma_scale_f32_16x16x128_f8f6f4 v[94:97], v[2:9], v[224:231], v[94:97], v192, v192 op_sel_hi:[0,0,0]
	v_mfma_scale_f32_16x16x128_f8f6f4 v[90:93], v[10:17], v[224:231], v[90:93], v192, v192 op_sel_hi:[0,0,0]
	s_setprio 0
	s_barrier
	s_mov_b32 m0, s46
	v_lshl_add_u64 v[164:165], s[34:35], 0, v[146:147]
	ds_read_b128 v[232:235], v179
	ds_read_b128 v[236:239], v180
	ds_read_b128 v[240:243], v181
	ds_read_b128 v[244:247], v182
	global_load_lds_dwordx4 v[164:165], off
	v_lshl_add_u64 v[166:167], s[34:35], 0, v[148:149]
	s_mov_b32 m0, s47
	s_nop 0
	global_load_lds_dwordx4 v[166:167], off
	s_barrier
	s_waitcnt lgkmcnt(0)
	s_setprio 1
	s_waitcnt lgkmcnt(0)
	v_mfma_scale_f32_16x16x128_f8f6f4 v[134:137], v[232:239], v[194:201], v[134:137], v192, v192 op_sel_hi:[0,0,0]
	v_mfma_scale_f32_16x16x128_f8f6f4 v[130:133], v[240:247], v[194:201], v[130:133], v192, v192 op_sel_hi:[0,0,0]
	v_mfma_scale_f32_16x16x128_f8f6f4 v[118:121], v[232:239], v[202:209], v[118:121], v192, v192 op_sel_hi:[0,0,0]
	v_mfma_scale_f32_16x16x128_f8f6f4 v[114:117], v[240:247], v[202:209], v[114:117], v192, v192 op_sel_hi:[0,0,0]
	v_mfma_scale_f32_16x16x128_f8f6f4 v[102:105], v[232:239], v[216:223], v[102:105], v192, v192 op_sel_hi:[0,0,0]
	v_mfma_scale_f32_16x16x128_f8f6f4 v[98:101], v[240:247], v[216:223], v[98:101], v192, v192 op_sel_hi:[0,0,0]
	v_mfma_scale_f32_16x16x128_f8f6f4 v[86:89], v[232:239], v[224:231], v[86:89], v192, v192 op_sel_hi:[0,0,0]
	v_mfma_scale_f32_16x16x128_f8f6f4 v[82:85], v[240:247], v[224:231], v[82:85], v192, v192 op_sel_hi:[0,0,0]
	s_setprio 0
	s_mov_b32 m0, s45
	v_lshl_add_u64 v[168:169], s[36:37], 0, v[146:147]
	s_barrier
	ds_read_b128 v[194:197], v191 offset:16384
	ds_read_b128 v[198:201], v191 offset:17408
	ds_read_b128 v[202:205], v191 offset:18432
	ds_read_b128 v[206:209], v191 offset:19456
	ds_read_b128 v[216:219], v191 offset:20480
	ds_read_b128 v[220:223], v191 offset:21504
	ds_read_b128 v[224:227], v191 offset:22528
	ds_read_b128 v[228:231], v191 offset:23552
	global_load_lds_dwordx4 v[168:169], off
	v_lshl_add_u64 v[170:171], s[36:37], 0, v[148:149]
	s_mov_b32 m0, s50
	s_nop 0
	global_load_lds_dwordx4 v[170:171], off
	s_barrier
	s_waitcnt lgkmcnt(0)
	s_setprio 1
	s_waitcnt lgkmcnt(0)
	v_mfma_scale_f32_16x16x128_f8f6f4 v[78:81], v[2:9], v[194:201], v[78:81], v192, v192 op_sel_hi:[0,0,0]
	v_mfma_scale_f32_16x16x128_f8f6f4 v[74:77], v[10:17], v[194:201], v[74:77], v192, v192 op_sel_hi:[0,0,0]
	v_mfma_scale_f32_16x16x128_f8f6f4 v[62:65], v[2:9], v[202:209], v[62:65], v192, v192 op_sel_hi:[0,0,0]
	v_mfma_scale_f32_16x16x128_f8f6f4 v[58:61], v[10:17], v[202:209], v[58:61], v192, v192 op_sel_hi:[0,0,0]
	v_mfma_scale_f32_16x16x128_f8f6f4 v[46:49], v[2:9], v[216:223], v[46:49], v192, v192 op_sel_hi:[0,0,0]
	v_mfma_scale_f32_16x16x128_f8f6f4 v[42:45], v[10:17], v[216:223], v[42:45], v192, v192 op_sel_hi:[0,0,0]
	v_mfma_scale_f32_16x16x128_f8f6f4 v[30:33], v[2:9], v[224:231], v[30:33], v192, v192 op_sel_hi:[0,0,0]
	v_mfma_scale_f32_16x16x128_f8f6f4 v[26:29], v[10:17], v[224:231], v[26:29], v192, v192 op_sel_hi:[0,0,0]
	s_setprio 0
	s_barrier
	s_add_u32 s70, s34, 0x40000
	s_addc_u32 s71, s35, 0
	s_mov_b32 m0, s51
	v_lshl_add_u64 v[2:3], s[70:71], 0, v[146:147]
	global_load_lds_dwordx4 v[2:3], off
	v_lshl_add_u64 v[2:3], s[70:71], 0, v[148:149]
	s_mov_b32 m0, s52
	s_nop 0
	global_load_lds_dwordx4 v[2:3], off
	s_waitcnt vmcnt(6)
	s_barrier
	s_setprio 1
	v_mfma_scale_f32_16x16x128_f8f6f4 v[70:73], v[232:239], v[194:201], v[70:73], v192, v192 op_sel_hi:[0,0,0]
	v_mfma_scale_f32_16x16x128_f8f6f4 v[66:69], v[240:247], v[194:201], v[66:69], v192, v192 op_sel_hi:[0,0,0]
	v_mfma_scale_f32_16x16x128_f8f6f4 v[54:57], v[232:239], v[202:209], v[54:57], v192, v192 op_sel_hi:[0,0,0]
	v_mfma_scale_f32_16x16x128_f8f6f4 v[50:53], v[240:247], v[202:209], v[50:53], v192, v192 op_sel_hi:[0,0,0]
	v_mfma_scale_f32_16x16x128_f8f6f4 v[38:41], v[232:239], v[216:223], v[38:41], v192, v192 op_sel_hi:[0,0,0]
	v_mfma_scale_f32_16x16x128_f8f6f4 v[34:37], v[240:247], v[216:223], v[34:37], v192, v192 op_sel_hi:[0,0,0]
	v_mfma_scale_f32_16x16x128_f8f6f4 v[22:25], v[232:239], v[224:231], v[22:25], v192, v192 op_sel_hi:[0,0,0]
	v_mfma_scale_f32_16x16x128_f8f6f4 v[18:21], v[240:247], v[224:231], v[18:21], v192, v192 op_sel_hi:[0,0,0]
	s_setprio 0
	s_barrier
	ds_read_b128 v[2:5], v183
	ds_read_b128 v[6:9], v184
	ds_read_b128 v[10:13], v185
	ds_read_b128 v[14:17], v186
	s_add_u32 s36, s36, 0x40000
	s_addc_u32 s37, s37, 0
	s_mov_b32 m0, s53
	v_lshl_add_u64 v[210:211], s[36:37], 0, v[146:147]
	ds_read_b128 v[194:197], v191 offset:32768
	ds_read_b128 v[198:201], v191 offset:33792
	ds_read_b128 v[202:205], v191 offset:34816
	ds_read_b128 v[206:209], v191 offset:35840
	ds_read_b128 v[216:219], v191 offset:36864
	ds_read_b128 v[220:223], v191 offset:37888
	ds_read_b128 v[224:227], v191 offset:38912
	ds_read_b128 v[228:231], v191 offset:39936
	global_load_lds_dwordx4 v[210:211], off
	v_lshl_add_u64 v[210:211], s[36:37], 0, v[148:149]
	s_mov_b32 m0, s54
	s_nop 0
	global_load_lds_dwordx4 v[210:211], off
	s_waitcnt lgkmcnt(8)
	s_barrier
	s_waitcnt lgkmcnt(0)
	s_setprio 1
	s_waitcnt lgkmcnt(0)
	v_mfma_scale_f32_16x16x128_f8f6f4 v[142:145], v[2:9], v[194:201], v[142:145], v192, v192 op_sel_hi:[0,0,0]
	v_mfma_scale_f32_16x16x128_f8f6f4 v[138:141], v[10:17], v[194:201], v[138:141], v192, v192 op_sel_hi:[0,0,0]
	v_mfma_scale_f32_16x16x128_f8f6f4 v[126:129], v[2:9], v[202:209], v[126:129], v192, v192 op_sel_hi:[0,0,0]
	v_mfma_scale_f32_16x16x128_f8f6f4 v[122:125], v[10:17], v[202:209], v[122:125], v192, v192 op_sel_hi:[0,0,0]
	v_mfma_scale_f32_16x16x128_f8f6f4 v[110:113], v[2:9], v[216:223], v[110:113], v192, v192 op_sel_hi:[0,0,0]
	v_mfma_scale_f32_16x16x128_f8f6f4 v[106:109], v[10:17], v[216:223], v[106:109], v192, v192 op_sel_hi:[0,0,0]
	v_mfma_scale_f32_16x16x128_f8f6f4 v[94:97], v[2:9], v[224:231], v[94:97], v192, v192 op_sel_hi:[0,0,0]
	v_mfma_scale_f32_16x16x128_f8f6f4 v[90:93], v[10:17], v[224:231], v[90:93], v192, v192 op_sel_hi:[0,0,0]
	s_setprio 0
	s_barrier
	s_mov_b32 m0, s58
	v_lshl_add_u64 v[164:165], v[164:165], 0, s[14:15]
	ds_read_b128 v[232:235], v187
	ds_read_b128 v[236:239], v188
	ds_read_b128 v[240:243], v189
	ds_read_b128 v[244:247], v190
	global_load_lds_dwordx4 v[164:165], off
	v_lshl_add_u64 v[164:165], v[166:167], 0, s[14:15]
	s_mov_b32 m0, s59
	s_nop 0
	global_load_lds_dwordx4 v[164:165], off
	s_barrier
	s_waitcnt lgkmcnt(0)
	s_setprio 1
	s_waitcnt lgkmcnt(0)
	v_mfma_scale_f32_16x16x128_f8f6f4 v[134:137], v[232:239], v[194:201], v[134:137], v192, v192 op_sel_hi:[0,0,0]
	v_mfma_scale_f32_16x16x128_f8f6f4 v[130:133], v[240:247], v[194:201], v[130:133], v192, v192 op_sel_hi:[0,0,0]
	v_mfma_scale_f32_16x16x128_f8f6f4 v[118:121], v[232:239], v[202:209], v[118:121], v192, v192 op_sel_hi:[0,0,0]
	v_mfma_scale_f32_16x16x128_f8f6f4 v[114:117], v[240:247], v[202:209], v[114:117], v192, v192 op_sel_hi:[0,0,0]
	v_mfma_scale_f32_16x16x128_f8f6f4 v[102:105], v[232:239], v[216:223], v[102:105], v192, v192 op_sel_hi:[0,0,0]
	v_mfma_scale_f32_16x16x128_f8f6f4 v[98:101], v[240:247], v[216:223], v[98:101], v192, v192 op_sel_hi:[0,0,0]
	v_mfma_scale_f32_16x16x128_f8f6f4 v[86:89], v[232:239], v[224:231], v[86:89], v192, v192 op_sel_hi:[0,0,0]
	v_mfma_scale_f32_16x16x128_f8f6f4 v[82:85], v[240:247], v[224:231], v[82:85], v192, v192 op_sel_hi:[0,0,0]
	s_setprio 0
	s_mov_b32 m0, s60
	v_lshl_add_u64 v[164:165], v[168:169], 0, s[14:15]
	s_barrier
	ds_read_b128 v[194:197], v191 offset:49152
	ds_read_b128 v[198:201], v191 offset:50176
	ds_read_b128 v[202:205], v191 offset:51200
	ds_read_b128 v[206:209], v191 offset:52224
	ds_read_b128 v[216:219], v191 offset:53248
	ds_read_b128 v[220:223], v191 offset:54272
	ds_read_b128 v[224:227], v191 offset:55296
	ds_read_b128 v[228:231], v191 offset:56320
	global_load_lds_dwordx4 v[164:165], off
	v_lshl_add_u64 v[164:165], v[170:171], 0, s[14:15]
	s_mov_b32 m0, s61
	s_nop 0
	global_load_lds_dwordx4 v[164:165], off
	s_barrier
	s_waitcnt lgkmcnt(0)
	s_setprio 1
	s_waitcnt lgkmcnt(0)
	v_mfma_scale_f32_16x16x128_f8f6f4 v[78:81], v[2:9], v[194:201], v[78:81], v192, v192 op_sel_hi:[0,0,0]
	v_mfma_scale_f32_16x16x128_f8f6f4 v[74:77], v[10:17], v[194:201], v[74:77], v192, v192 op_sel_hi:[0,0,0]
	v_mfma_scale_f32_16x16x128_f8f6f4 v[62:65], v[2:9], v[202:209], v[62:65], v192, v192 op_sel_hi:[0,0,0]
	v_mfma_scale_f32_16x16x128_f8f6f4 v[58:61], v[10:17], v[202:209], v[58:61], v192, v192 op_sel_hi:[0,0,0]
	v_mfma_scale_f32_16x16x128_f8f6f4 v[46:49], v[2:9], v[216:223], v[46:49], v192, v192 op_sel_hi:[0,0,0]
	v_mfma_scale_f32_16x16x128_f8f6f4 v[42:45], v[10:17], v[216:223], v[42:45], v192, v192 op_sel_hi:[0,0,0]
	v_mfma_scale_f32_16x16x128_f8f6f4 v[30:33], v[2:9], v[224:231], v[30:33], v192, v192 op_sel_hi:[0,0,0]
	v_mfma_scale_f32_16x16x128_f8f6f4 v[26:29], v[10:17], v[224:231], v[26:29], v192, v192 op_sel_hi:[0,0,0]
	s_setprio 0
	s_barrier
	s_add_u32 s34, s34, 0x40080
	s_addc_u32 s35, s35, 0
	s_mov_b32 m0, s62
	v_lshl_add_u64 v[2:3], s[34:35], 0, v[146:147]
	global_load_lds_dwordx4 v[2:3], off
	v_lshl_add_u64 v[2:3], s[34:35], 0, v[148:149]
	s_mov_b32 m0, s63
	s_nop 0
	global_load_lds_dwordx4 v[2:3], off
	s_waitcnt vmcnt(6)
	s_barrier
	s_setprio 1
	v_mfma_scale_f32_16x16x128_f8f6f4 v[70:73], v[232:239], v[194:201], v[70:73], v192, v192 op_sel_hi:[0,0,0]
	v_mfma_scale_f32_16x16x128_f8f6f4 v[66:69], v[240:247], v[194:201], v[66:69], v192, v192 op_sel_hi:[0,0,0]
	v_mfma_scale_f32_16x16x128_f8f6f4 v[54:57], v[232:239], v[202:209], v[54:57], v192, v192 op_sel_hi:[0,0,0]
	v_mfma_scale_f32_16x16x128_f8f6f4 v[50:53], v[240:247], v[202:209], v[50:53], v192, v192 op_sel_hi:[0,0,0]
	v_mfma_scale_f32_16x16x128_f8f6f4 v[38:41], v[232:239], v[216:223], v[38:41], v192, v192 op_sel_hi:[0,0,0]
	v_mfma_scale_f32_16x16x128_f8f6f4 v[34:37], v[240:247], v[216:223], v[34:37], v192, v192 op_sel_hi:[0,0,0]
	v_mfma_scale_f32_16x16x128_f8f6f4 v[22:25], v[232:239], v[224:231], v[22:25], v192, v192 op_sel_hi:[0,0,0]
	v_mfma_scale_f32_16x16x128_f8f6f4 v[18:21], v[240:247], v[224:231], v[18:21], v192, v192 op_sel_hi:[0,0,0]
	s_setprio 0
	s_add_i32 s68, s68, 2
	s_add_u32 s30, s30, 0x100
	s_addc_u32 s31, s31, 0
	s_add_u32 s66, s66, 0x100
	s_addc_u32 s67, s67, 0
	s_cmp_gt_u32 s68, 13
	s_barrier
	s_cbranch_scc0 .LBB0_465
	s_lshl_b32 s23, s10, 8
	s_nop 15
	s_nop 15
	s_add_i32 s23, s23, s57
	v_or_b32_e32 v12, s23, v172
	v_cmp_gt_i32_e32 vcc, s56, v12
	v_mov_b32_e32 v195, 0
	v_mov_b32_e32 v194, 1.0
	v_mov_b32_e32 v196, 1.0
	v_mov_b32_e32 v197, 0
	v_mov_b32_e32 v198, 1.0
	v_mov_b32_e32 v199, 0
	v_mov_b32_e32 v200, 1.0
	v_mov_b32_e32 v201, 0
	s_and_saveexec_b64 s[98:99], vcc
	s_cbranch_execz .Lrope_a_1
	s_bfe_u32 s25, s23, 0x50006
	v_mov_b32_e32 v194, s25
	v_cndmask_b32_e64 v194, v172, v194, s[4:5]
	v_lshlrev_b32_e32 v194, 8, v194
	v_mov_b32_e32 v195, v151
	v_lshl_add_u64 v[198:199], v[154:155], 0, v[194:195]
	global_load_dwordx4 v[194:197], v[198:199], off offset:16
	s_nop 0
	global_load_dwordx4 v[198:201], v[198:199], off
.Lrope_a_1:
	s_or_b64 exec, exec, s[98:99]
	v_or_b32_e32 v12, s23, v173
	v_cmp_gt_i32_e32 vcc, s56, v12
	v_mov_b32_e32 v203, 0
	v_mov_b32_e32 v202, 1.0
	v_mov_b32_e32 v204, 1.0
	v_mov_b32_e32 v205, 0
	v_mov_b32_e32 v206, 1.0
	v_mov_b32_e32 v207, 0
	v_mov_b32_e32 v208, 1.0
	v_mov_b32_e32 v209, 0
	s_and_saveexec_b64 s[98:99], vcc
	s_cbranch_execz .Lrope_a_2
	s_bfe_u32 s25, s23, 0x50006
	v_mov_b32_e32 v202, s25
	v_cndmask_b32_e64 v202, v173, v202, s[4:5]
	v_lshlrev_b32_e32 v202, 8, v202
	v_mov_b32_e32 v203, v151
	v_lshl_add_u64 v[206:207], v[154:155], 0, v[202:203]
	global_load_dwordx4 v[202:205], v[206:207], off offset:16
	s_nop 0
	global_load_dwordx4 v[206:209], v[206:207], off
.Lrope_a_2:
	s_or_b64 exec, exec, s[98:99]
	v_or_b32_e32 v12, s23, v174
	v_cmp_gt_i32_e32 vcc, s56, v12
	v_mov_b32_e32 v217, 0
	v_mov_b32_e32 v216, 1.0
	v_mov_b32_e32 v218, 1.0
	v_mov_b32_e32 v219, 0
	v_mov_b32_e32 v220, 1.0
	v_mov_b32_e32 v221, 0
	v_mov_b32_e32 v222, 1.0
	v_mov_b32_e32 v223, 0
	s_and_saveexec_b64 s[98:99], vcc
	s_cbranch_execz .Lrope_a_3
	s_bfe_u32 s25, s23, 0x50006
	v_mov_b32_e32 v216, s25
	v_cndmask_b32_e64 v216, v174, v216, s[4:5]
	v_lshlrev_b32_e32 v216, 8, v216
	v_mov_b32_e32 v217, v151
	v_lshl_add_u64 v[220:221], v[154:155], 0, v[216:217]
	global_load_dwordx4 v[216:219], v[220:221], off offset:16
	s_nop 0
	global_load_dwordx4 v[220:223], v[220:221], off
.Lrope_a_3:
	s_or_b64 exec, exec, s[98:99]
	s_add_i32 s100, s23, 0x80
	v_or_b32_e32 v12, s100, v1
	v_cmp_gt_i32_e32 vcc, s56, v12
	v_mov_b32_e32 v225, 0
	v_mov_b32_e32 v224, 1.0
	v_mov_b32_e32 v226, 1.0
	v_mov_b32_e32 v227, 0
	v_mov_b32_e32 v228, 1.0
	v_mov_b32_e32 v229, 0
	v_mov_b32_e32 v230, 1.0
	v_mov_b32_e32 v231, 0
	s_and_saveexec_b64 s[98:99], vcc
	s_cbranch_execz .Lrope_a_4
	s_bfe_u32 s25, s100, 0x50006
	v_mov_b32_e32 v224, s25
	v_cndmask_b32_e64 v224, v1, v224, s[4:5]
	v_lshlrev_b32_e32 v224, 8, v224
	v_mov_b32_e32 v225, v151
	v_lshl_add_u64 v[228:229], v[154:155], 0, v[224:225]
	global_load_dwordx4 v[224:227], v[228:229], off offset:16
	s_nop 0
	global_load_dwordx4 v[228:231], v[228:229], off
.Lrope_a_4:
	s_or_b64 exec, exec, s[98:99]
	s_add_i32 s100, s23, 0x80
	v_or_b32_e32 v12, s100, v172
	v_cmp_gt_i32_e32 vcc, s56, v12
	v_mov_b32_e32 v233, 0
	v_mov_b32_e32 v232, 1.0
	v_mov_b32_e32 v234, 1.0
	v_mov_b32_e32 v235, 0
	v_mov_b32_e32 v236, 1.0
	v_mov_b32_e32 v237, 0
	v_mov_b32_e32 v238, 1.0
	v_mov_b32_e32 v239, 0
	s_and_saveexec_b64 s[98:99], vcc
	s_cbranch_execz .Lrope_a_5
	s_bfe_u32 s25, s100, 0x50006
	v_mov_b32_e32 v232, s25
	v_cndmask_b32_e64 v232, v172, v232, s[4:5]
	v_lshlrev_b32_e32 v232, 8, v232
	v_mov_b32_e32 v233, v151
	v_lshl_add_u64 v[236:237], v[154:155], 0, v[232:233]
	global_load_dwordx4 v[232:235], v[236:237], off offset:16
	s_nop 0
	global_load_dwordx4 v[236:239], v[236:237], off
.Lrope_a_5:
	s_or_b64 exec, exec, s[98:99]
	s_add_i32 s100, s23, 0x80
	v_or_b32_e32 v12, s100, v173
	v_cmp_gt_i32_e32 vcc, s56, v12
	v_mov_b32_e32 v241, 0
	v_mov_b32_e32 v240, 1.0
	v_mov_b32_e32 v242, 1.0
	v_mov_b32_e32 v243, 0
	v_mov_b32_e32 v244, 1.0
	v_mov_b32_e32 v245, 0
	v_mov_b32_e32 v246, 1.0
	v_mov_b32_e32 v247, 0
	s_and_saveexec_b64 s[98:99], vcc
	s_cbranch_execz .Lrope_a_6
	s_bfe_u32 s25, s100, 0x50006
	v_mov_b32_e32 v240, s25
	v_cndmask_b32_e64 v240, v173, v240, s[4:5]
	v_lshlrev_b32_e32 v240, 8, v240
	v_mov_b32_e32 v241, v151
	v_lshl_add_u64 v[244:245], v[154:155], 0, v[240:241]
	global_load_dwordx4 v[240:243], v[244:245], off offset:16
	s_nop 0
	global_load_dwordx4 v[244:247], v[244:245], off
.Lrope_a_6:
	s_or_b64 exec, exec, s[98:99]
	v_or_b32_e32 v12, s23, v1
	v_cmp_gt_i32_e32 vcc, s56, v12
	v_mov_b32_e32 v3, 0
	v_mov_b32_e32 v2, 1.0
	v_mov_b32_e32 v4, 1.0
	v_mov_b32_e32 v5, 0
	v_mov_b32_e32 v6, 1.0
	v_mov_b32_e32 v7, 0
	v_mov_b32_e32 v8, 1.0
	v_mov_b32_e32 v9, 0
	s_and_saveexec_b64 s[10:11], vcc
	s_cbranch_execz .LBB0_468
	s_bfe_u32 s9, s23, 0x50006
	v_mov_b32_e32 v2, s9
	v_cndmask_b32_e64 v2, v1, v2, s[4:5]
	v_lshlrev_b32_e32 v150, 8, v2
	v_lshl_add_u64 v[6:7], v[154:155], 0, v[150:151]
	global_load_dwordx4 v[2:5], v[6:7], off offset:16
	s_nop 0
	global_load_dwordx4 v[6:9], v[6:7], off

.LBB0_482:
	v_mul_f32_e32 v130, v122, v199
	v_fma_f32 v130, v126, v198, -v130
	v_mul_f32_e32 v126, v126, v199
	v_fmac_f32_e32 v126, v122, v198
	v_mul_f32_e32 v122, v123, v201
	v_fma_f32 v122, v127, v200, -v122
	v_mul_f32_e32 v127, v127, v201
	v_fmac_f32_e32 v127, v123, v200
	v_mul_f32_e32 v123, v124, v195
	v_fma_f32 v123, v128, v194, -v123
	v_mul_f32_e32 v128, v128, v195
	v_fmac_f32_e32 v128, v124, v194
	v_mul_f32_e32 v124, v125, v197
	v_fma_f32 v124, v129, v196, -v124
	v_mul_f32_e32 v129, v129, v197
	v_cvt_pk_bf16_f32 v122, v130, v122
	v_cvt_pk_bf16_f32 v123, v123, v124
	v_fmac_f32_e32 v129, v125, v196
	v_cvt_pk_bf16_f32 v124, v126, v127
	v_cvt_pk_bf16_f32 v125, v128, v129
	global_store_dwordx2 v[16:17], v[122:123], off
	global_store_dwordx2 v[16:17], v[124:125], off offset:32
	v_cndmask_b32_e64 v16, 0, 1, s[34:35]
	v_cmp_ne_u32_e64 s[10:11], 1, v16
	s_andn2_b64 vcc, exec, s[34:35]
	s_mov_b64 s[34:35], -1
	s_cbranch_vccnz .LBB0_484
	v_lshl_add_u64 v[14:15], v[150:151], 1, v[14:15]
	v_lshl_add_u64 v[16:17], v[14:15], 0, s[20:21]
	s_mov_b64 s[34:35], 0

.LBB0_492:
	v_mul_f32_e32 v114, v106, v207
	v_fma_f32 v114, v110, v206, -v114
	v_mul_f32_e32 v110, v110, v207
	v_fmac_f32_e32 v110, v106, v206
	v_mul_f32_e32 v106, v107, v209
	v_fma_f32 v106, v111, v208, -v106
	v_mul_f32_e32 v111, v111, v209
	v_fmac_f32_e32 v111, v107, v208
	v_mul_f32_e32 v107, v108, v203
	v_fma_f32 v107, v112, v202, -v107
	v_mul_f32_e32 v112, v112, v203
	v_fmac_f32_e32 v112, v108, v202
	v_mul_f32_e32 v108, v109, v205
	v_fma_f32 v108, v113, v204, -v108
	v_mul_f32_e32 v113, v113, v205
	v_cvt_pk_bf16_f32 v106, v114, v106
	v_cvt_pk_bf16_f32 v107, v107, v108
	s_and_b64 vcc, exec, s[10:11]
	s_mov_b64 s[34:35], -1
	v_fmac_f32_e32 v113, v109, v204
	v_cvt_pk_bf16_f32 v108, v110, v111
	v_cvt_pk_bf16_f32 v109, v112, v113
	global_store_dwordx2 v[16:17], v[106:107], off
	global_store_dwordx2 v[16:17], v[108:109], off offset:32
	s_cbranch_vccnz .LBB0_494
	v_lshl_add_u64 v[14:15], v[150:151], 1, v[14:15]
	v_lshl_add_u64 v[16:17], v[14:15], 0, s[20:21]
	s_mov_b64 s[34:35], 0

.LBB0_496:
	v_mul_f32_e32 v12, v98, v207
	v_mul_f32_e32 v207, v102, v207
	v_fma_f32 v12, v102, v206, -v12
	v_fmac_f32_e32 v207, v98, v206
	v_mul_f32_e32 v206, v99, v209
	v_mul_f32_e32 v209, v103, v209
	v_fma_f32 v206, v103, v208, -v206
	v_fmac_f32_e32 v209, v99, v208
	v_mul_f32_e32 v208, v100, v203
	v_mul_f32_e32 v13, v104, v203
	v_fma_f32 v208, v104, v202, -v208
	v_fmac_f32_e32 v13, v100, v202
	v_mul_f32_e32 v202, v101, v205
	v_fma_f32 v203, v105, v204, -v202
	v_mul_f32_e32 v205, v105, v205
	v_fmac_f32_e32 v205, v101, v204
	v_cvt_pk_bf16_f32 v202, v12, v206
	v_cvt_pk_bf16_f32 v203, v208, v203
	v_cvt_pk_bf16_f32 v204, v207, v209
	v_cvt_pk_bf16_f32 v205, v13, v205
	global_store_dwordx2 v[16:17], v[202:203], off
	global_store_dwordx2 v[16:17], v[204:205], off offset:32
	v_or_b32_e32 v12, s23, v174
	v_ashrrev_i32_e32 v13, 31, v12
	v_lshlrev_b64 v[14:15], 10, v[12:13]
	s_mov_b64 s[34:35], -1
	s_and_b64 vcc, exec, s[8:9]
	v_lshl_add_u64 v[14:15], s[12:13], 0, v[14:15]
	s_cbranch_vccnz .LBB0_500
	v_mov_b32_e32 v16, v10
	v_mov_b32_e32 v17, v151
	v_lshl_add_u64 v[16:17], v[16:17], 1, v[14:15]
	v_lshl_add_u64 v[16:17], v[16:17], 0, s[18:19]
	s_mov_b64 s[34:35], 0

.LBB0_502:
	v_mul_f32_e32 v98, v90, v221
	v_fma_f32 v98, v94, v220, -v98
	v_mul_f32_e32 v94, v94, v221
	v_fmac_f32_e32 v94, v90, v220
	v_mul_f32_e32 v90, v91, v223
	v_fma_f32 v90, v95, v222, -v90
	v_mul_f32_e32 v95, v95, v223
	v_fmac_f32_e32 v95, v91, v222
	v_mul_f32_e32 v91, v92, v217
	v_fma_f32 v91, v96, v216, -v91
	v_mul_f32_e32 v96, v96, v217
	v_fmac_f32_e32 v96, v92, v216
	v_mul_f32_e32 v92, v93, v219
	v_fma_f32 v92, v97, v218, -v92
	v_mul_f32_e32 v97, v97, v219
	v_cvt_pk_bf16_f32 v90, v98, v90
	v_cvt_pk_bf16_f32 v91, v91, v92
	s_and_b64 vcc, exec, s[10:11]
	s_mov_b64 s[34:35], -1
	v_fmac_f32_e32 v97, v93, v218
	v_cvt_pk_bf16_f32 v92, v94, v95
	v_cvt_pk_bf16_f32 v93, v96, v97
	global_store_dwordx2 v[16:17], v[90:91], off
	global_store_dwordx2 v[16:17], v[92:93], off offset:32
	s_cbranch_vccnz .LBB0_504
	v_lshl_add_u64 v[14:15], v[150:151], 1, v[14:15]
	v_lshl_add_u64 v[16:17], v[14:15], 0, s[20:21]
	s_mov_b64 s[34:35], 0

.LBB0_506:
	v_mul_f32_e32 v12, v82, v221
	v_mul_f32_e32 v221, v86, v221
	v_fma_f32 v12, v86, v220, -v12
	v_fmac_f32_e32 v221, v82, v220
	v_mul_f32_e32 v220, v83, v223
	v_mul_f32_e32 v223, v87, v223
	v_fma_f32 v220, v87, v222, -v220
	v_fmac_f32_e32 v223, v83, v222
	v_mul_f32_e32 v222, v84, v217
	v_mul_f32_e32 v13, v88, v217
	v_fma_f32 v222, v88, v216, -v222
	v_fmac_f32_e32 v13, v84, v216
	v_mul_f32_e32 v216, v85, v219
	v_fma_f32 v217, v89, v218, -v216
	v_mul_f32_e32 v219, v89, v219
	v_fmac_f32_e32 v219, v85, v218
	v_cvt_pk_bf16_f32 v216, v12, v220
	v_cvt_pk_bf16_f32 v217, v222, v217
	v_cvt_pk_bf16_f32 v218, v221, v223
	v_cvt_pk_bf16_f32 v219, v13, v219
	global_store_dwordx2 v[16:17], v[216:217], off
	global_store_dwordx2 v[16:17], v[218:219], off offset:32
	s_addk_i32 s23, 0x80
	v_or_b32_e32 v12, s23, v1
	v_ashrrev_i32_e32 v13, 31, v12
	v_lshlrev_b64 v[14:15], 10, v[12:13]
	s_mov_b64 s[34:35], -1
	s_and_b64 vcc, exec, s[8:9]
	v_lshl_add_u64 v[14:15], s[12:13], 0, v[14:15]
	s_cbranch_vccnz .LBB0_510
	v_mov_b32_e32 v16, v10
	v_mov_b32_e32 v17, v151
	v_lshl_add_u64 v[16:17], v[16:17], 1, v[14:15]
	v_lshl_add_u64 v[16:17], v[16:17], 0, s[18:19]
	s_mov_b64 s[34:35], 0

.LBB0_512:
	v_mul_f32_e32 v82, v74, v229
	v_fma_f32 v82, v78, v228, -v82
	v_mul_f32_e32 v78, v78, v229
	v_fmac_f32_e32 v78, v74, v228
	v_mul_f32_e32 v74, v75, v231
	v_fma_f32 v74, v79, v230, -v74
	v_mul_f32_e32 v79, v79, v231
	v_fmac_f32_e32 v79, v75, v230
	v_mul_f32_e32 v75, v76, v225
	v_fma_f32 v75, v80, v224, -v75
	v_mul_f32_e32 v80, v80, v225
	v_fmac_f32_e32 v80, v76, v224
	v_mul_f32_e32 v76, v77, v227
	v_fma_f32 v76, v81, v226, -v76
	v_mul_f32_e32 v81, v81, v227
	v_cvt_pk_bf16_f32 v74, v82, v74
	v_cvt_pk_bf16_f32 v75, v75, v76
	s_and_b64 vcc, exec, s[10:11]
	s_mov_b64 s[34:35], -1
	v_fmac_f32_e32 v81, v77, v226
	v_cvt_pk_bf16_f32 v76, v78, v79
	v_cvt_pk_bf16_f32 v77, v80, v81
	global_store_dwordx2 v[16:17], v[74:75], off
	global_store_dwordx2 v[16:17], v[76:77], off offset:32
	s_cbranch_vccnz .LBB0_514
	v_lshl_add_u64 v[14:15], v[150:151], 1, v[14:15]
	v_lshl_add_u64 v[16:17], v[14:15], 0, s[20:21]
	s_mov_b64 s[34:35], 0

.LBB0_516:
	v_mul_f32_e32 v12, v66, v229
	v_mul_f32_e32 v229, v70, v229
	v_fma_f32 v12, v70, v228, -v12
	v_fmac_f32_e32 v229, v66, v228
	v_mul_f32_e32 v228, v67, v231
	v_mul_f32_e32 v231, v71, v231
	v_fma_f32 v228, v71, v230, -v228
	v_fmac_f32_e32 v231, v67, v230
	v_mul_f32_e32 v230, v68, v225
	v_mul_f32_e32 v13, v72, v225
	v_fma_f32 v230, v72, v224, -v230
	v_fmac_f32_e32 v13, v68, v224
	v_mul_f32_e32 v224, v69, v227
	v_fma_f32 v225, v73, v226, -v224
	v_mul_f32_e32 v227, v73, v227
	v_fmac_f32_e32 v227, v69, v226
	v_cvt_pk_bf16_f32 v224, v12, v228
	v_cvt_pk_bf16_f32 v225, v230, v225
	v_cvt_pk_bf16_f32 v226, v229, v231
	v_cvt_pk_bf16_f32 v227, v13, v227
	global_store_dwordx2 v[16:17], v[224:225], off
	global_store_dwordx2 v[16:17], v[226:227], off offset:32
	v_or_b32_e32 v12, s23, v172
	v_ashrrev_i32_e32 v13, 31, v12
	v_lshlrev_b64 v[14:15], 10, v[12:13]
	s_mov_b64 s[34:35], -1
	s_and_b64 vcc, exec, s[8:9]
	v_lshl_add_u64 v[14:15], s[12:13], 0, v[14:15]
	s_cbranch_vccnz .LBB0_520
	v_mov_b32_e32 v16, v10
	v_mov_b32_e32 v17, v151
	v_lshl_add_u64 v[16:17], v[16:17], 1, v[14:15]
	v_lshl_add_u64 v[16:17], v[16:17], 0, s[18:19]
	s_mov_b64 s[34:35], 0

.LBB0_522:
	v_mul_f32_e32 v66, v58, v237
	v_fma_f32 v66, v62, v236, -v66
	v_mul_f32_e32 v62, v62, v237
	v_fmac_f32_e32 v62, v58, v236
	v_mul_f32_e32 v58, v59, v239
	v_fma_f32 v58, v63, v238, -v58
	v_mul_f32_e32 v63, v63, v239
	v_fmac_f32_e32 v63, v59, v238
	v_mul_f32_e32 v59, v60, v233
	v_fma_f32 v59, v64, v232, -v59
	v_mul_f32_e32 v64, v64, v233
	v_fmac_f32_e32 v64, v60, v232
	v_mul_f32_e32 v60, v61, v235
	v_fma_f32 v60, v65, v234, -v60
	v_mul_f32_e32 v65, v65, v235
	v_cvt_pk_bf16_f32 v58, v66, v58
	v_cvt_pk_bf16_f32 v59, v59, v60
	s_and_b64 vcc, exec, s[10:11]
	s_mov_b64 s[34:35], -1
	v_fmac_f32_e32 v65, v61, v234
	v_cvt_pk_bf16_f32 v60, v62, v63
	v_cvt_pk_bf16_f32 v61, v64, v65
	global_store_dwordx2 v[16:17], v[58:59], off
	global_store_dwordx2 v[16:17], v[60:61], off offset:32
	s_cbranch_vccnz .LBB0_524
	v_lshl_add_u64 v[14:15], v[150:151], 1, v[14:15]
	v_lshl_add_u64 v[16:17], v[14:15], 0, s[20:21]
	s_mov_b64 s[34:35], 0

.LBB0_526:
	v_mul_f32_e32 v12, v50, v237
	v_mul_f32_e32 v237, v54, v237
	v_fma_f32 v12, v54, v236, -v12
	v_fmac_f32_e32 v237, v50, v236
	v_mul_f32_e32 v236, v51, v239
	v_mul_f32_e32 v239, v55, v239
	v_fma_f32 v236, v55, v238, -v236
	v_fmac_f32_e32 v239, v51, v238
	v_mul_f32_e32 v238, v52, v233
	v_mul_f32_e32 v13, v56, v233
	v_fma_f32 v238, v56, v232, -v238
	v_fmac_f32_e32 v13, v52, v232
	v_mul_f32_e32 v232, v53, v235
	v_fma_f32 v233, v57, v234, -v232
	v_mul_f32_e32 v235, v57, v235
	v_fmac_f32_e32 v235, v53, v234
	v_cvt_pk_bf16_f32 v232, v12, v236
	v_cvt_pk_bf16_f32 v233, v238, v233
	v_cvt_pk_bf16_f32 v234, v237, v239
	v_cvt_pk_bf16_f32 v235, v13, v235
	global_store_dwordx2 v[16:17], v[232:233], off
	global_store_dwordx2 v[16:17], v[234:235], off offset:32
	v_or_b32_e32 v12, s23, v173
	v_ashrrev_i32_e32 v13, 31, v12
	v_lshlrev_b64 v[14:15], 10, v[12:13]
	s_mov_b64 s[34:35], -1
	s_and_b64 vcc, exec, s[8:9]
	v_lshl_add_u64 v[14:15], s[12:13], 0, v[14:15]
	s_cbranch_vccnz .LBB0_530
	v_mov_b32_e32 v16, v10
	v_mov_b32_e32 v17, v151
	v_lshl_add_u64 v[16:17], v[16:17], 1, v[14:15]
	v_lshl_add_u64 v[16:17], v[16:17], 0, s[18:19]
	s_mov_b64 s[34:35], 0

.LBB0_532:
	v_mul_f32_e32 v50, v42, v245
	v_fma_f32 v50, v46, v244, -v50
	v_mul_f32_e32 v46, v46, v245
	v_fmac_f32_e32 v46, v42, v244
	v_mul_f32_e32 v42, v43, v247
	v_fma_f32 v42, v47, v246, -v42
	v_mul_f32_e32 v47, v47, v247
	v_fmac_f32_e32 v47, v43, v246
	v_mul_f32_e32 v43, v44, v241
	v_fma_f32 v43, v48, v240, -v43
	v_mul_f32_e32 v48, v48, v241
	v_fmac_f32_e32 v48, v44, v240
	v_mul_f32_e32 v44, v45, v243
	v_fma_f32 v44, v49, v242, -v44
	v_mul_f32_e32 v49, v49, v243
	v_cvt_pk_bf16_f32 v42, v50, v42
	v_cvt_pk_bf16_f32 v43, v43, v44
	s_and_b64 vcc, exec, s[10:11]
	s_mov_b64 s[34:35], -1
	v_fmac_f32_e32 v49, v45, v242
	v_cvt_pk_bf16_f32 v44, v46, v47
	v_cvt_pk_bf16_f32 v45, v48, v49
	global_store_dwordx2 v[16:17], v[42:43], off
	global_store_dwordx2 v[16:17], v[44:45], off offset:32
	s_cbranch_vccnz .LBB0_534
	v_lshl_add_u64 v[14:15], v[150:151], 1, v[14:15]
	v_lshl_add_u64 v[16:17], v[14:15], 0, s[20:21]
	s_mov_b64 s[34:35], 0

.LBB0_536:
	v_mul_f32_e32 v12, v34, v245
	v_mul_f32_e32 v245, v38, v245
	v_fma_f32 v12, v38, v244, -v12
	v_fmac_f32_e32 v245, v34, v244
	v_mul_f32_e32 v244, v35, v247
	v_mul_f32_e32 v247, v39, v247
	v_fma_f32 v244, v39, v246, -v244
	v_fmac_f32_e32 v247, v35, v246
	v_mul_f32_e32 v246, v36, v241
	v_mul_f32_e32 v13, v40, v241
	v_fma_f32 v246, v40, v240, -v246
	v_fmac_f32_e32 v13, v36, v240
	v_mul_f32_e32 v240, v37, v243
	v_fma_f32 v241, v41, v242, -v240
	v_mul_f32_e32 v243, v41, v243
	v_fmac_f32_e32 v243, v37, v242
	v_cvt_pk_bf16_f32 v240, v12, v244
	v_cvt_pk_bf16_f32 v241, v246, v241
	v_cvt_pk_bf16_f32 v242, v245, v247
	v_cvt_pk_bf16_f32 v243, v13, v243
	global_store_dwordx2 v[16:17], v[240:241], off
	global_store_dwordx2 v[16:17], v[242:243], off offset:32
	v_or_b32_e32 v12, s23, v174
	v_cmp_gt_i32_e32 vcc, s56, v12
	v_mov_b32_e32 v7, 0
	v_mov_b32_e32 v6, 1.0
	v_mov_b32_e32 v8, 1.0
	v_mov_b32_e32 v9, 0
	v_mov_b32_e32 v2, 1.0
	v_mov_b32_e32 v3, 0
	v_mov_b32_e32 v4, 1.0
	v_mov_b32_e32 v5, 0
	s_and_saveexec_b64 s[34:35], vcc
	s_cbranch_execz .LBB0_538
	s_bfe_u32 s23, s23, 0x50006
	v_mov_b32_e32 v2, s23
	v_cndmask_b32_e64 v2, v174, v2, s[4:5]
	v_lshlrev_b32_e32 v2, 8, v2
	v_mov_b32_e32 v3, v151
	v_lshl_add_u64 v[2:3], v[154:155], 0, v[2:3]
	global_load_dwordx4 v[6:9], v[2:3], off offset:16
	s_nop 0
	global_load_dwordx4 v[2:5], v[2:3], off

.LBB0_2368:
	ds_read_b128 v[2:5], v176
	ds_read_b128 v[6:9], v177
	ds_read_b128 v[10:13], v178
	ds_read_b128 v[14:17], v179
	s_add_u32 s36, s34, 0xfffc0080
	s_addc_u32 s37, s35, -1
	s_cmp_eq_u32 s71, 12
	s_cselect_b32 s39, s11, s37
	s_cselect_b32 s38, s13, s36
	s_cselect_b32 s37, s25, s70
	s_cselect_b32 s36, s27, s69
	v_lshl_add_u64 v[164:165], s[34:35], 0, v[156:157]
	s_add_i32 m0, s47, 0xc000
	ds_read_b128 v[194:197], v192
	ds_read_b128 v[198:201], v192 offset:1024
	ds_read_b128 v[216:219], v192 offset:2048
	ds_read_b128 v[220:223], v192 offset:3072
	ds_read_b128 v[224:227], v192 offset:4096
	ds_read_b128 v[228:231], v192 offset:5120
	ds_read_b128 v[232:235], v192 offset:6144
	ds_read_b128 v[236:239], v192 offset:7168
	global_load_lds_dwordx4 v[164:165], off
	v_lshl_add_u64 v[164:165], s[34:35], 0, v[158:159]
	s_add_i32 m0, s47, 0xe000
	s_nop 0
	global_load_lds_dwordx4 v[164:165], off
	s_waitcnt lgkmcnt(8)
	s_barrier
	s_waitcnt lgkmcnt(0)
	s_setprio 1
	s_waitcnt lgkmcnt(0)
	v_mfma_scale_f32_16x16x128_f8f6f4 v[142:145], v[2:9], v[194:201], v[142:145], v193, v193 op_sel_hi:[0,0,0]
	v_mfma_scale_f32_16x16x128_f8f6f4 v[138:141], v[10:17], v[194:201], v[138:141], v193, v193 op_sel_hi:[0,0,0]
	v_mfma_scale_f32_16x16x128_f8f6f4 v[126:129], v[2:9], v[216:223], v[126:129], v193, v193 op_sel_hi:[0,0,0]
	v_mfma_scale_f32_16x16x128_f8f6f4 v[122:125], v[10:17], v[216:223], v[122:125], v193, v193 op_sel_hi:[0,0,0]
	v_mfma_scale_f32_16x16x128_f8f6f4 v[110:113], v[2:9], v[224:231], v[110:113], v193, v193 op_sel_hi:[0,0,0]
	v_mfma_scale_f32_16x16x128_f8f6f4 v[106:109], v[10:17], v[224:231], v[106:109], v193, v193 op_sel_hi:[0,0,0]
	v_mfma_scale_f32_16x16x128_f8f6f4 v[94:97], v[2:9], v[232:239], v[94:97], v193, v193 op_sel_hi:[0,0,0]
	v_mfma_scale_f32_16x16x128_f8f6f4 v[90:93], v[10:17], v[232:239], v[90:93], v193, v193 op_sel_hi:[0,0,0]
	s_setprio 0
	s_barrier
	s_mov_b32 m0, s52
	v_lshl_add_u64 v[164:165], s[36:37], 0, v[146:147]
	ds_read_b128 v[240:243], v180
	ds_read_b128 v[244:247], v181
	ds_read_b128 v[202:205], v182
	ds_read_b128 v[206:209], v183
	global_load_lds_dwordx4 v[164:165], off
	v_lshl_add_u64 v[166:167], s[36:37], 0, v[148:149]
	s_mov_b32 m0, s53
	s_nop 0
	global_load_lds_dwordx4 v[166:167], off
	s_barrier
	s_waitcnt lgkmcnt(0)
	s_setprio 1
	s_waitcnt lgkmcnt(0)
	v_mfma_scale_f32_16x16x128_f8f6f4 v[134:137], v[240:247], v[194:201], v[134:137], v193, v193 op_sel_hi:[0,0,0]
	v_mfma_scale_f32_16x16x128_f8f6f4 v[130:133], v[202:209], v[194:201], v[130:133], v193, v193 op_sel_hi:[0,0,0]
	v_mfma_scale_f32_16x16x128_f8f6f4 v[118:121], v[240:247], v[216:223], v[118:121], v193, v193 op_sel_hi:[0,0,0]
	v_mfma_scale_f32_16x16x128_f8f6f4 v[114:117], v[202:209], v[216:223], v[114:117], v193, v193 op_sel_hi:[0,0,0]
	v_mfma_scale_f32_16x16x128_f8f6f4 v[102:105], v[240:247], v[224:231], v[102:105], v193, v193 op_sel_hi:[0,0,0]
	v_mfma_scale_f32_16x16x128_f8f6f4 v[98:101], v[202:209], v[224:231], v[98:101], v193, v193 op_sel_hi:[0,0,0]
	v_mfma_scale_f32_16x16x128_f8f6f4 v[86:89], v[240:247], v[232:239], v[86:89], v193, v193 op_sel_hi:[0,0,0]
	v_mfma_scale_f32_16x16x128_f8f6f4 v[82:85], v[202:209], v[232:239], v[82:85], v193, v193 op_sel_hi:[0,0,0]
	s_setprio 0
	s_mov_b32 m0, s47
	v_lshl_add_u64 v[168:169], s[38:39], 0, v[146:147]
	s_barrier
	ds_read_b128 v[194:197], v192 offset:16384
	ds_read_b128 v[198:201], v192 offset:17408
	ds_read_b128 v[216:219], v192 offset:18432
	ds_read_b128 v[220:223], v192 offset:19456
	ds_read_b128 v[224:227], v192 offset:20480
	ds_read_b128 v[228:231], v192 offset:21504
	ds_read_b128 v[232:235], v192 offset:22528
	ds_read_b128 v[236:239], v192 offset:23552
	global_load_lds_dwordx4 v[168:169], off
	v_lshl_add_u64 v[170:171], s[38:39], 0, v[148:149]
	s_mov_b32 m0, s54
	s_nop 0
	global_load_lds_dwordx4 v[170:171], off
	s_barrier
	s_waitcnt lgkmcnt(0)
	s_setprio 1
	s_waitcnt lgkmcnt(0)
	v_mfma_scale_f32_16x16x128_f8f6f4 v[78:81], v[2:9], v[194:201], v[78:81], v193, v193 op_sel_hi:[0,0,0]
	v_mfma_scale_f32_16x16x128_f8f6f4 v[74:77], v[10:17], v[194:201], v[74:77], v193, v193 op_sel_hi:[0,0,0]
	v_mfma_scale_f32_16x16x128_f8f6f4 v[62:65], v[2:9], v[216:223], v[62:65], v193, v193 op_sel_hi:[0,0,0]
	v_mfma_scale_f32_16x16x128_f8f6f4 v[58:61], v[10:17], v[216:223], v[58:61], v193, v193 op_sel_hi:[0,0,0]
	v_mfma_scale_f32_16x16x128_f8f6f4 v[46:49], v[2:9], v[224:231], v[46:49], v193, v193 op_sel_hi:[0,0,0]
	v_mfma_scale_f32_16x16x128_f8f6f4 v[42:45], v[10:17], v[224:231], v[42:45], v193, v193 op_sel_hi:[0,0,0]
	v_mfma_scale_f32_16x16x128_f8f6f4 v[30:33], v[2:9], v[232:239], v[30:33], v193, v193 op_sel_hi:[0,0,0]
	v_mfma_scale_f32_16x16x128_f8f6f4 v[26:29], v[10:17], v[232:239], v[26:29], v193, v193 op_sel_hi:[0,0,0]
	s_setprio 0
	s_barrier
	s_add_u32 s78, s36, 0x40000
	s_addc_u32 s79, s37, 0
	s_mov_b32 m0, s55
	v_lshl_add_u64 v[2:3], s[78:79], 0, v[146:147]
	global_load_lds_dwordx4 v[2:3], off
	v_lshl_add_u64 v[2:3], s[78:79], 0, v[148:149]
	s_mov_b32 m0, s56
	s_nop 0
	global_load_lds_dwordx4 v[2:3], off
	s_waitcnt vmcnt(6)
	s_barrier
	s_setprio 1
	v_mfma_scale_f32_16x16x128_f8f6f4 v[70:73], v[240:247], v[194:201], v[70:73], v193, v193 op_sel_hi:[0,0,0]
	v_mfma_scale_f32_16x16x128_f8f6f4 v[66:69], v[202:209], v[194:201], v[66:69], v193, v193 op_sel_hi:[0,0,0]
	v_mfma_scale_f32_16x16x128_f8f6f4 v[54:57], v[240:247], v[216:223], v[54:57], v193, v193 op_sel_hi:[0,0,0]
	v_mfma_scale_f32_16x16x128_f8f6f4 v[50:53], v[202:209], v[216:223], v[50:53], v193, v193 op_sel_hi:[0,0,0]
	v_mfma_scale_f32_16x16x128_f8f6f4 v[38:41], v[240:247], v[224:231], v[38:41], v193, v193 op_sel_hi:[0,0,0]
	v_mfma_scale_f32_16x16x128_f8f6f4 v[34:37], v[202:209], v[224:231], v[34:37], v193, v193 op_sel_hi:[0,0,0]
	v_mfma_scale_f32_16x16x128_f8f6f4 v[22:25], v[240:247], v[232:239], v[22:25], v193, v193 op_sel_hi:[0,0,0]
	v_mfma_scale_f32_16x16x128_f8f6f4 v[18:21], v[202:209], v[232:239], v[18:21], v193, v193 op_sel_hi:[0,0,0]
	s_setprio 0
	s_barrier
	ds_read_b128 v[2:5], v184
	ds_read_b128 v[6:9], v185
	ds_read_b128 v[10:13], v186
	ds_read_b128 v[14:17], v187
	s_add_u32 s38, s38, 0x40000
	s_addc_u32 s39, s39, 0
	s_mov_b32 m0, s57
	v_lshl_add_u64 v[232:233], s[38:39], 0, v[146:147]
	ds_read_b128 v[194:197], v192 offset:32768
	ds_read_b128 v[198:201], v192 offset:33792
	ds_read_b128 v[202:205], v192 offset:34816
	ds_read_b128 v[206:209], v192 offset:35840
	ds_read_b128 v[216:219], v192 offset:36864
	ds_read_b128 v[220:223], v192 offset:37888
	ds_read_b128 v[224:227], v192 offset:38912
	ds_read_b128 v[228:231], v192 offset:39936
	global_load_lds_dwordx4 v[232:233], off
	v_lshl_add_u64 v[232:233], s[38:39], 0, v[148:149]
	s_mov_b32 m0, s58
	s_nop 0
	global_load_lds_dwordx4 v[232:233], off
	s_waitcnt lgkmcnt(8)
	s_barrier
	s_waitcnt lgkmcnt(0)
	s_setprio 1
	s_waitcnt lgkmcnt(0)
	v_mfma_scale_f32_16x16x128_f8f6f4 v[142:145], v[2:9], v[194:201], v[142:145], v193, v193 op_sel_hi:[0,0,0]
	v_mfma_scale_f32_16x16x128_f8f6f4 v[138:141], v[10:17], v[194:201], v[138:141], v193, v193 op_sel_hi:[0,0,0]
	v_mfma_scale_f32_16x16x128_f8f6f4 v[126:129], v[2:9], v[202:209], v[126:129], v193, v193 op_sel_hi:[0,0,0]
	v_mfma_scale_f32_16x16x128_f8f6f4 v[122:125], v[10:17], v[202:209], v[122:125], v193, v193 op_sel_hi:[0,0,0]
	v_mfma_scale_f32_16x16x128_f8f6f4 v[110:113], v[2:9], v[216:223], v[110:113], v193, v193 op_sel_hi:[0,0,0]
	v_mfma_scale_f32_16x16x128_f8f6f4 v[106:109], v[10:17], v[216:223], v[106:109], v193, v193 op_sel_hi:[0,0,0]
	v_mfma_scale_f32_16x16x128_f8f6f4 v[94:97], v[2:9], v[224:231], v[94:97], v193, v193 op_sel_hi:[0,0,0]
	v_mfma_scale_f32_16x16x128_f8f6f4 v[90:93], v[10:17], v[224:231], v[90:93], v193, v193 op_sel_hi:[0,0,0]
	s_setprio 0
	s_barrier
	s_mov_b32 m0, s62
	v_lshl_add_u64 v[164:165], v[164:165], 0, s[16:17]
	ds_read_b128 v[232:235], v188
	ds_read_b128 v[236:239], v189
	ds_read_b128 v[240:243], v190
	ds_read_b128 v[244:247], v191
	global_load_lds_dwordx4 v[164:165], off
	v_lshl_add_u64 v[164:165], v[166:167], 0, s[16:17]
	s_mov_b32 m0, s63
	s_nop 0
	global_load_lds_dwordx4 v[164:165], off
	s_barrier
	s_waitcnt lgkmcnt(0)
	s_setprio 1
	s_waitcnt lgkmcnt(0)
	v_mfma_scale_f32_16x16x128_f8f6f4 v[134:137], v[232:239], v[194:201], v[134:137], v193, v193 op_sel_hi:[0,0,0]
	v_mfma_scale_f32_16x16x128_f8f6f4 v[130:133], v[240:247], v[194:201], v[130:133], v193, v193 op_sel_hi:[0,0,0]
	v_mfma_scale_f32_16x16x128_f8f6f4 v[118:121], v[232:239], v[202:209], v[118:121], v193, v193 op_sel_hi:[0,0,0]
	v_mfma_scale_f32_16x16x128_f8f6f4 v[114:117], v[240:247], v[202:209], v[114:117], v193, v193 op_sel_hi:[0,0,0]
	v_mfma_scale_f32_16x16x128_f8f6f4 v[102:105], v[232:239], v[216:223], v[102:105], v193, v193 op_sel_hi:[0,0,0]
	v_mfma_scale_f32_16x16x128_f8f6f4 v[98:101], v[240:247], v[216:223], v[98:101], v193, v193 op_sel_hi:[0,0,0]
	v_mfma_scale_f32_16x16x128_f8f6f4 v[86:89], v[232:239], v[224:231], v[86:89], v193, v193 op_sel_hi:[0,0,0]
	v_mfma_scale_f32_16x16x128_f8f6f4 v[82:85], v[240:247], v[224:231], v[82:85], v193, v193 op_sel_hi:[0,0,0]
	s_setprio 0
	s_mov_b32 m0, s64
	v_lshl_add_u64 v[164:165], v[168:169], 0, s[16:17]
	s_barrier
	ds_read_b128 v[194:197], v192 offset:49152
	ds_read_b128 v[198:201], v192 offset:50176
	ds_read_b128 v[202:205], v192 offset:51200
	ds_read_b128 v[206:209], v192 offset:52224
	ds_read_b128 v[216:219], v192 offset:53248
	ds_read_b128 v[220:223], v192 offset:54272
	ds_read_b128 v[224:227], v192 offset:55296
	ds_read_b128 v[228:231], v192 offset:56320
	global_load_lds_dwordx4 v[164:165], off
	v_lshl_add_u64 v[164:165], v[170:171], 0, s[16:17]
	s_mov_b32 m0, s65
	s_nop 0
	global_load_lds_dwordx4 v[164:165], off
	s_barrier
	s_waitcnt lgkmcnt(0)
	s_setprio 1
	s_waitcnt lgkmcnt(0)
	v_mfma_scale_f32_16x16x128_f8f6f4 v[78:81], v[2:9], v[194:201], v[78:81], v193, v193 op_sel_hi:[0,0,0]
	v_mfma_scale_f32_16x16x128_f8f6f4 v[74:77], v[10:17], v[194:201], v[74:77], v193, v193 op_sel_hi:[0,0,0]
	v_mfma_scale_f32_16x16x128_f8f6f4 v[62:65], v[2:9], v[202:209], v[62:65], v193, v193 op_sel_hi:[0,0,0]
	v_mfma_scale_f32_16x16x128_f8f6f4 v[58:61], v[10:17], v[202:209], v[58:61], v193, v193 op_sel_hi:[0,0,0]
	v_mfma_scale_f32_16x16x128_f8f6f4 v[46:49], v[2:9], v[216:223], v[46:49], v193, v193 op_sel_hi:[0,0,0]
	v_mfma_scale_f32_16x16x128_f8f6f4 v[42:45], v[10:17], v[216:223], v[42:45], v193, v193 op_sel_hi:[0,0,0]
	v_mfma_scale_f32_16x16x128_f8f6f4 v[30:33], v[2:9], v[224:231], v[30:33], v193, v193 op_sel_hi:[0,0,0]
	v_mfma_scale_f32_16x16x128_f8f6f4 v[26:29], v[10:17], v[224:231], v[26:29], v193, v193 op_sel_hi:[0,0,0]
	s_setprio 0
	s_barrier
	s_add_u32 s36, s36, 0x40080
	s_addc_u32 s37, s37, 0
	s_mov_b32 m0, s66
	v_lshl_add_u64 v[2:3], s[36:37], 0, v[146:147]
	global_load_lds_dwordx4 v[2:3], off
	v_lshl_add_u64 v[2:3], s[36:37], 0, v[148:149]
	s_mov_b32 m0, s67
	s_nop 0
	global_load_lds_dwordx4 v[2:3], off
	s_waitcnt vmcnt(6)
	s_barrier
	s_setprio 1
	v_mfma_scale_f32_16x16x128_f8f6f4 v[70:73], v[232:239], v[194:201], v[70:73], v193, v193 op_sel_hi:[0,0,0]
	v_mfma_scale_f32_16x16x128_f8f6f4 v[66:69], v[240:247], v[194:201], v[66:69], v193, v193 op_sel_hi:[0,0,0]
	v_mfma_scale_f32_16x16x128_f8f6f4 v[54:57], v[232:239], v[202:209], v[54:57], v193, v193 op_sel_hi:[0,0,0]
	v_mfma_scale_f32_16x16x128_f8f6f4 v[50:53], v[240:247], v[202:209], v[50:53], v193, v193 op_sel_hi:[0,0,0]
	v_mfma_scale_f32_16x16x128_f8f6f4 v[38:41], v[232:239], v[216:223], v[38:41], v193, v193 op_sel_hi:[0,0,0]
	v_mfma_scale_f32_16x16x128_f8f6f4 v[34:37], v[240:247], v[216:223], v[34:37], v193, v193 op_sel_hi:[0,0,0]
	v_mfma_scale_f32_16x16x128_f8f6f4 v[22:25], v[232:239], v[224:231], v[22:25], v193, v193 op_sel_hi:[0,0,0]
	v_mfma_scale_f32_16x16x128_f8f6f4 v[18:21], v[240:247], v[224:231], v[18:21], v193, v193 op_sel_hi:[0,0,0]
	s_setprio 0
	s_add_i32 s71, s71, 2
	s_add_u32 s34, s34, 0x100
	s_addc_u32 s35, s35, 0
	s_add_u32 s69, s69, 0x100
	s_addc_u32 s70, s70, 0
	s_cmp_gt_u32 s71, 13
	s_barrier
	s_cbranch_scc0 .LBB0_2368
	s_lshl_b32 s25, s12, 8
	s_nop 15
	s_nop 15
	s_add_i32 s25, s25, s61
	v_or_b32_e32 v12, s25, v173
	v_cmp_gt_i32_e32 vcc, s60, v12
	v_mov_b32_e32 v195, 0
	v_mov_b32_e32 v194, 1.0
	v_mov_b32_e32 v196, 1.0
	v_mov_b32_e32 v197, 0
	v_mov_b32_e32 v198, 1.0
	v_mov_b32_e32 v199, 0
	v_mov_b32_e32 v200, 1.0
	v_mov_b32_e32 v201, 0
	s_and_saveexec_b64 s[98:99], vcc
	s_cbranch_execz .Lrope_b_1
	s_bfe_u32 s27, s25, 0x50006
	v_mov_b32_e32 v194, s27
	v_cndmask_b32_e64 v194, v173, v194, s[6:7]
	v_lshlrev_b32_e32 v194, 8, v194
	v_mov_b32_e32 v195, v151
	v_lshl_add_u64 v[198:199], v[154:155], 0, v[194:195]
	global_load_dwordx4 v[194:197], v[198:199], off offset:16
	s_nop 0
	global_load_dwordx4 v[198:201], v[198:199], off
.Lrope_b_1:
	s_or_b64 exec, exec, s[98:99]
	v_or_b32_e32 v12, s25, v174
	v_cmp_gt_i32_e32 vcc, s60, v12
	v_mov_b32_e32 v203, 0
	v_mov_b32_e32 v202, 1.0
	v_mov_b32_e32 v204, 1.0
	v_mov_b32_e32 v205, 0
	v_mov_b32_e32 v206, 1.0
	v_mov_b32_e32 v207, 0
	v_mov_b32_e32 v208, 1.0
	v_mov_b32_e32 v209, 0
	s_and_saveexec_b64 s[98:99], vcc
	s_cbranch_execz .Lrope_b_2
	s_bfe_u32 s27, s25, 0x50006
	v_mov_b32_e32 v202, s27
	v_cndmask_b32_e64 v202, v174, v202, s[6:7]
	v_lshlrev_b32_e32 v202, 8, v202
	v_mov_b32_e32 v203, v151
	v_lshl_add_u64 v[206:207], v[154:155], 0, v[202:203]
	global_load_dwordx4 v[202:205], v[206:207], off offset:16
	s_nop 0
	global_load_dwordx4 v[206:209], v[206:207], off
.Lrope_b_2:
	s_or_b64 exec, exec, s[98:99]
	v_or_b32_e32 v12, s25, v175
	v_cmp_gt_i32_e32 vcc, s60, v12
	v_mov_b32_e32 v217, 0
	v_mov_b32_e32 v216, 1.0
	v_mov_b32_e32 v218, 1.0
	v_mov_b32_e32 v219, 0
	v_mov_b32_e32 v220, 1.0
	v_mov_b32_e32 v221, 0
	v_mov_b32_e32 v222, 1.0
	v_mov_b32_e32 v223, 0
	s_and_saveexec_b64 s[98:99], vcc
	s_cbranch_execz .Lrope_b_3
	s_bfe_u32 s27, s25, 0x50006
	v_mov_b32_e32 v216, s27
	v_cndmask_b32_e64 v216, v175, v216, s[6:7]
	v_lshlrev_b32_e32 v216, 8, v216
	v_mov_b32_e32 v217, v151
	v_lshl_add_u64 v[220:221], v[154:155], 0, v[216:217]
	global_load_dwordx4 v[216:219], v[220:221], off offset:16
	s_nop 0
	global_load_dwordx4 v[220:223], v[220:221], off
.Lrope_b_3:
	s_or_b64 exec, exec, s[98:99]
	s_add_i32 s100, s25, 0x80
	v_or_b32_e32 v12, s100, v172
	v_cmp_gt_i32_e32 vcc, s60, v12
	v_mov_b32_e32 v225, 0
	v_mov_b32_e32 v224, 1.0
	v_mov_b32_e32 v226, 1.0
	v_mov_b32_e32 v227, 0
	v_mov_b32_e32 v228, 1.0
	v_mov_b32_e32 v229, 0
	v_mov_b32_e32 v230, 1.0
	v_mov_b32_e32 v231, 0
	s_and_saveexec_b64 s[98:99], vcc
	s_cbranch_execz .Lrope_b_4
	s_bfe_u32 s27, s100, 0x50006
	v_mov_b32_e32 v224, s27
	v_cndmask_b32_e64 v224, v172, v224, s[6:7]
	v_lshlrev_b32_e32 v224, 8, v224
	v_mov_b32_e32 v225, v151
	v_lshl_add_u64 v[228:229], v[154:155], 0, v[224:225]
	global_load_dwordx4 v[224:227], v[228:229], off offset:16
	s_nop 0
	global_load_dwordx4 v[228:231], v[228:229], off
.Lrope_b_4:
	s_or_b64 exec, exec, s[98:99]
	s_add_i32 s100, s25, 0x80
	v_or_b32_e32 v12, s100, v173
	v_cmp_gt_i32_e32 vcc, s60, v12
	v_mov_b32_e32 v233, 0
	v_mov_b32_e32 v232, 1.0
	v_mov_b32_e32 v234, 1.0
	v_mov_b32_e32 v235, 0
	v_mov_b32_e32 v236, 1.0
	v_mov_b32_e32 v237, 0
	v_mov_b32_e32 v238, 1.0
	v_mov_b32_e32 v239, 0
	s_and_saveexec_b64 s[98:99], vcc
	s_cbranch_execz .Lrope_b_5
	s_bfe_u32 s27, s100, 0x50006
	v_mov_b32_e32 v232, s27
	v_cndmask_b32_e64 v232, v173, v232, s[6:7]
	v_lshlrev_b32_e32 v232, 8, v232
	v_mov_b32_e32 v233, v151
	v_lshl_add_u64 v[236:237], v[154:155], 0, v[232:233]
	global_load_dwordx4 v[232:235], v[236:237], off offset:16
	s_nop 0
	global_load_dwordx4 v[236:239], v[236:237], off
.Lrope_b_5:
	s_or_b64 exec, exec, s[98:99]
	s_add_i32 s100, s25, 0x80
	v_or_b32_e32 v12, s100, v174
	v_cmp_gt_i32_e32 vcc, s60, v12
	v_mov_b32_e32 v241, 0
	v_mov_b32_e32 v240, 1.0
	v_mov_b32_e32 v242, 1.0
	v_mov_b32_e32 v243, 0
	v_mov_b32_e32 v244, 1.0
	v_mov_b32_e32 v245, 0
	v_mov_b32_e32 v246, 1.0
	v_mov_b32_e32 v247, 0
	s_and_saveexec_b64 s[98:99], vcc
	s_cbranch_execz .Lrope_b_6
	s_bfe_u32 s27, s100, 0x50006
	v_mov_b32_e32 v240, s27
	v_cndmask_b32_e64 v240, v174, v240, s[6:7]
	v_lshlrev_b32_e32 v240, 8, v240
	v_mov_b32_e32 v241, v151
	v_lshl_add_u64 v[244:245], v[154:155], 0, v[240:241]
	global_load_dwordx4 v[240:243], v[244:245], off offset:16
	s_nop 0
	global_load_dwordx4 v[244:247], v[244:245], off
.Lrope_b_6:
	s_or_b64 exec, exec, s[98:99]
	v_or_b32_e32 v12, s25, v172
	v_cmp_gt_i32_e32 vcc, s60, v12
	v_mov_b32_e32 v3, 0
	v_mov_b32_e32 v2, 1.0
	v_mov_b32_e32 v4, 1.0
	v_mov_b32_e32 v5, 0
	v_mov_b32_e32 v6, 1.0
	v_mov_b32_e32 v7, 0
	v_mov_b32_e32 v8, 1.0
	v_mov_b32_e32 v9, 0
	s_and_saveexec_b64 s[12:13], vcc
	s_cbranch_execz .LBB0_2371
	s_bfe_u32 s11, s25, 0x50006
	v_mov_b32_e32 v2, s11
	v_cndmask_b32_e64 v2, v172, v2, s[6:7]
	v_lshlrev_b32_e32 v150, 8, v2
	v_lshl_add_u64 v[6:7], v[154:155], 0, v[150:151]
	global_load_dwordx4 v[2:5], v[6:7], off offset:16
	s_nop 0
	global_load_dwordx4 v[6:9], v[6:7], off

.LBB0_2385:
	v_mul_f32_e32 v130, v122, v199
	v_fma_f32 v130, v126, v198, -v130
	v_mul_f32_e32 v126, v126, v199
	v_fmac_f32_e32 v126, v122, v198
	v_mul_f32_e32 v122, v123, v201
	v_fma_f32 v122, v127, v200, -v122
	v_mul_f32_e32 v127, v127, v201
	v_fmac_f32_e32 v127, v123, v200
	v_mul_f32_e32 v123, v124, v195
	v_fma_f32 v123, v128, v194, -v123
	v_mul_f32_e32 v128, v128, v195
	v_fmac_f32_e32 v128, v124, v194
	v_mul_f32_e32 v124, v125, v197
	v_fma_f32 v124, v129, v196, -v124
	v_mul_f32_e32 v129, v129, v197
	v_cvt_pk_bf16_f32 v122, v130, v122
	v_cvt_pk_bf16_f32 v123, v123, v124
	v_fmac_f32_e32 v129, v125, v196
	v_cvt_pk_bf16_f32 v124, v126, v127
	v_cvt_pk_bf16_f32 v125, v128, v129
	global_store_dwordx2 v[16:17], v[122:123], off
	global_store_dwordx2 v[16:17], v[124:125], off offset:32
	v_cndmask_b32_e64 v16, 0, 1, s[36:37]
	v_cmp_ne_u32_e64 s[12:13], 1, v16
	s_andn2_b64 vcc, exec, s[36:37]
	s_mov_b64 s[36:37], -1
	s_cbranch_vccnz .LBB0_2387
	v_lshl_add_u64 v[14:15], v[150:151], 1, v[14:15]
	v_lshl_add_u64 v[16:17], v[14:15], 0, s[22:23]
	s_mov_b64 s[36:37], 0

.LBB0_2395:
	v_mul_f32_e32 v114, v106, v207
	v_fma_f32 v114, v110, v206, -v114
	v_mul_f32_e32 v110, v110, v207
	v_fmac_f32_e32 v110, v106, v206
	v_mul_f32_e32 v106, v107, v209
	v_fma_f32 v106, v111, v208, -v106
	v_mul_f32_e32 v111, v111, v209
	v_fmac_f32_e32 v111, v107, v208
	v_mul_f32_e32 v107, v108, v203
	v_fma_f32 v107, v112, v202, -v107
	v_mul_f32_e32 v112, v112, v203
	v_fmac_f32_e32 v112, v108, v202
	v_mul_f32_e32 v108, v109, v205
	v_fma_f32 v108, v113, v204, -v108
	v_mul_f32_e32 v113, v113, v205
	v_cvt_pk_bf16_f32 v106, v114, v106
	v_cvt_pk_bf16_f32 v107, v107, v108
	s_and_b64 vcc, exec, s[12:13]
	s_mov_b64 s[36:37], -1
	v_fmac_f32_e32 v113, v109, v204
	v_cvt_pk_bf16_f32 v108, v110, v111
	v_cvt_pk_bf16_f32 v109, v112, v113
	global_store_dwordx2 v[16:17], v[106:107], off
	global_store_dwordx2 v[16:17], v[108:109], off offset:32
	s_cbranch_vccnz .LBB0_2397
	v_lshl_add_u64 v[14:15], v[150:151], 1, v[14:15]
	v_lshl_add_u64 v[16:17], v[14:15], 0, s[22:23]
	s_mov_b64 s[36:37], 0

.LBB0_2399:
	v_mul_f32_e32 v12, v98, v207
	v_mul_f32_e32 v207, v102, v207
	v_fma_f32 v12, v102, v206, -v12
	v_fmac_f32_e32 v207, v98, v206
	v_mul_f32_e32 v206, v99, v209
	v_mul_f32_e32 v209, v103, v209
	v_fma_f32 v206, v103, v208, -v206
	v_fmac_f32_e32 v209, v99, v208
	v_mul_f32_e32 v208, v100, v203
	v_mul_f32_e32 v13, v104, v203
	v_fma_f32 v208, v104, v202, -v208
	v_fmac_f32_e32 v13, v100, v202
	v_mul_f32_e32 v202, v101, v205
	v_fma_f32 v203, v105, v204, -v202
	v_mul_f32_e32 v205, v105, v205
	v_fmac_f32_e32 v205, v101, v204
	v_cvt_pk_bf16_f32 v202, v12, v206
	v_cvt_pk_bf16_f32 v203, v208, v203
	v_cvt_pk_bf16_f32 v204, v207, v209
	v_cvt_pk_bf16_f32 v205, v13, v205
	global_store_dwordx2 v[16:17], v[202:203], off
	global_store_dwordx2 v[16:17], v[204:205], off offset:32
	v_or_b32_e32 v12, s25, v175
	v_ashrrev_i32_e32 v13, 31, v12
	v_lshlrev_b64 v[14:15], 10, v[12:13]
	s_mov_b64 s[36:37], -1
	s_and_b64 vcc, exec, s[10:11]
	v_lshl_add_u64 v[14:15], s[14:15], 0, v[14:15]
	s_cbranch_vccnz .LBB0_2403
	v_mov_b32_e32 v16, v10
	v_mov_b32_e32 v17, v151
	v_lshl_add_u64 v[16:17], v[16:17], 1, v[14:15]
	v_lshl_add_u64 v[16:17], v[16:17], 0, s[20:21]
	s_mov_b64 s[36:37], 0

.LBB0_2405:
	v_mul_f32_e32 v98, v90, v221
	v_fma_f32 v98, v94, v220, -v98
	v_mul_f32_e32 v94, v94, v221
	v_fmac_f32_e32 v94, v90, v220
	v_mul_f32_e32 v90, v91, v223
	v_fma_f32 v90, v95, v222, -v90
	v_mul_f32_e32 v95, v95, v223
	v_fmac_f32_e32 v95, v91, v222
	v_mul_f32_e32 v91, v92, v217
	v_fma_f32 v91, v96, v216, -v91
	v_mul_f32_e32 v96, v96, v217
	v_fmac_f32_e32 v96, v92, v216
	v_mul_f32_e32 v92, v93, v219
	v_fma_f32 v92, v97, v218, -v92
	v_mul_f32_e32 v97, v97, v219
	v_cvt_pk_bf16_f32 v90, v98, v90
	v_cvt_pk_bf16_f32 v91, v91, v92
	s_and_b64 vcc, exec, s[12:13]
	s_mov_b64 s[36:37], -1
	v_fmac_f32_e32 v97, v93, v218
	v_cvt_pk_bf16_f32 v92, v94, v95
	v_cvt_pk_bf16_f32 v93, v96, v97
	global_store_dwordx2 v[16:17], v[90:91], off
	global_store_dwordx2 v[16:17], v[92:93], off offset:32
	s_cbranch_vccnz .LBB0_2407
	v_lshl_add_u64 v[14:15], v[150:151], 1, v[14:15]
	v_lshl_add_u64 v[16:17], v[14:15], 0, s[22:23]
	s_mov_b64 s[36:37], 0

.LBB0_2409:
	v_mul_f32_e32 v12, v82, v221
	v_mul_f32_e32 v221, v86, v221
	v_fma_f32 v12, v86, v220, -v12
	v_fmac_f32_e32 v221, v82, v220
	v_mul_f32_e32 v220, v83, v223
	v_mul_f32_e32 v223, v87, v223
	v_fma_f32 v220, v87, v222, -v220
	v_fmac_f32_e32 v223, v83, v222
	v_mul_f32_e32 v222, v84, v217
	v_mul_f32_e32 v13, v88, v217
	v_fma_f32 v222, v88, v216, -v222
	v_fmac_f32_e32 v13, v84, v216
	v_mul_f32_e32 v216, v85, v219
	v_fma_f32 v217, v89, v218, -v216
	v_mul_f32_e32 v219, v89, v219
	v_fmac_f32_e32 v219, v85, v218
	v_cvt_pk_bf16_f32 v216, v12, v220
	v_cvt_pk_bf16_f32 v217, v222, v217
	v_cvt_pk_bf16_f32 v218, v221, v223
	v_cvt_pk_bf16_f32 v219, v13, v219
	global_store_dwordx2 v[16:17], v[216:217], off
	global_store_dwordx2 v[16:17], v[218:219], off offset:32
	s_addk_i32 s25, 0x80
	v_or_b32_e32 v12, s25, v172
	v_ashrrev_i32_e32 v13, 31, v12
	v_lshlrev_b64 v[14:15], 10, v[12:13]
	s_mov_b64 s[36:37], -1
	s_and_b64 vcc, exec, s[10:11]
	v_lshl_add_u64 v[14:15], s[14:15], 0, v[14:15]
	s_cbranch_vccnz .LBB0_2413
	v_mov_b32_e32 v16, v10
	v_mov_b32_e32 v17, v151
	v_lshl_add_u64 v[16:17], v[16:17], 1, v[14:15]
	v_lshl_add_u64 v[16:17], v[16:17], 0, s[20:21]
	s_mov_b64 s[36:37], 0

.LBB0_2415:
	v_mul_f32_e32 v82, v74, v229
	v_fma_f32 v82, v78, v228, -v82
	v_mul_f32_e32 v78, v78, v229
	v_fmac_f32_e32 v78, v74, v228
	v_mul_f32_e32 v74, v75, v231
	v_fma_f32 v74, v79, v230, -v74
	v_mul_f32_e32 v79, v79, v231
	v_fmac_f32_e32 v79, v75, v230
	v_mul_f32_e32 v75, v76, v225
	v_fma_f32 v75, v80, v224, -v75
	v_mul_f32_e32 v80, v80, v225
	v_fmac_f32_e32 v80, v76, v224
	v_mul_f32_e32 v76, v77, v227
	v_fma_f32 v76, v81, v226, -v76
	v_mul_f32_e32 v81, v81, v227
	v_cvt_pk_bf16_f32 v74, v82, v74
	v_cvt_pk_bf16_f32 v75, v75, v76
	s_and_b64 vcc, exec, s[12:13]
	s_mov_b64 s[36:37], -1
	v_fmac_f32_e32 v81, v77, v226
	v_cvt_pk_bf16_f32 v76, v78, v79
	v_cvt_pk_bf16_f32 v77, v80, v81
	global_store_dwordx2 v[16:17], v[74:75], off
	global_store_dwordx2 v[16:17], v[76:77], off offset:32
	s_cbranch_vccnz .LBB0_2417
	v_lshl_add_u64 v[14:15], v[150:151], 1, v[14:15]
	v_lshl_add_u64 v[16:17], v[14:15], 0, s[22:23]
	s_mov_b64 s[36:37], 0

.LBB0_2419:
	v_mul_f32_e32 v12, v66, v229
	v_mul_f32_e32 v229, v70, v229
	v_fma_f32 v12, v70, v228, -v12
	v_fmac_f32_e32 v229, v66, v228
	v_mul_f32_e32 v228, v67, v231
	v_mul_f32_e32 v231, v71, v231
	v_fma_f32 v228, v71, v230, -v228
	v_fmac_f32_e32 v231, v67, v230
	v_mul_f32_e32 v230, v68, v225
	v_mul_f32_e32 v13, v72, v225
	v_fma_f32 v230, v72, v224, -v230
	v_fmac_f32_e32 v13, v68, v224
	v_mul_f32_e32 v224, v69, v227
	v_fma_f32 v225, v73, v226, -v224
	v_mul_f32_e32 v227, v73, v227
	v_fmac_f32_e32 v227, v69, v226
	v_cvt_pk_bf16_f32 v224, v12, v228
	v_cvt_pk_bf16_f32 v225, v230, v225
	v_cvt_pk_bf16_f32 v226, v229, v231
	v_cvt_pk_bf16_f32 v227, v13, v227
	global_store_dwordx2 v[16:17], v[224:225], off
	global_store_dwordx2 v[16:17], v[226:227], off offset:32
	v_or_b32_e32 v12, s25, v173
	v_ashrrev_i32_e32 v13, 31, v12
	v_lshlrev_b64 v[14:15], 10, v[12:13]
	s_mov_b64 s[36:37], -1
	s_and_b64 vcc, exec, s[10:11]
	v_lshl_add_u64 v[14:15], s[14:15], 0, v[14:15]
	s_cbranch_vccnz .LBB0_2423
	v_mov_b32_e32 v16, v10
	v_mov_b32_e32 v17, v151
	v_lshl_add_u64 v[16:17], v[16:17], 1, v[14:15]
	v_lshl_add_u64 v[16:17], v[16:17], 0, s[20:21]
	s_mov_b64 s[36:37], 0

.LBB0_2425:
	v_mul_f32_e32 v66, v58, v237
	v_fma_f32 v66, v62, v236, -v66
	v_mul_f32_e32 v62, v62, v237
	v_fmac_f32_e32 v62, v58, v236
	v_mul_f32_e32 v58, v59, v239
	v_fma_f32 v58, v63, v238, -v58
	v_mul_f32_e32 v63, v63, v239
	v_fmac_f32_e32 v63, v59, v238
	v_mul_f32_e32 v59, v60, v233
	v_fma_f32 v59, v64, v232, -v59
	v_mul_f32_e32 v64, v64, v233
	v_fmac_f32_e32 v64, v60, v232
	v_mul_f32_e32 v60, v61, v235
	v_fma_f32 v60, v65, v234, -v60
	v_mul_f32_e32 v65, v65, v235
	v_cvt_pk_bf16_f32 v58, v66, v58
	v_cvt_pk_bf16_f32 v59, v59, v60
	s_and_b64 vcc, exec, s[12:13]
	s_mov_b64 s[36:37], -1
	v_fmac_f32_e32 v65, v61, v234
	v_cvt_pk_bf16_f32 v60, v62, v63
	v_cvt_pk_bf16_f32 v61, v64, v65
	global_store_dwordx2 v[16:17], v[58:59], off
	global_store_dwordx2 v[16:17], v[60:61], off offset:32
	s_cbranch_vccnz .LBB0_2427
	v_lshl_add_u64 v[14:15], v[150:151], 1, v[14:15]
	v_lshl_add_u64 v[16:17], v[14:15], 0, s[22:23]
	s_mov_b64 s[36:37], 0

.LBB0_2429:
	v_mul_f32_e32 v12, v50, v237
	v_mul_f32_e32 v237, v54, v237
	v_fma_f32 v12, v54, v236, -v12
	v_fmac_f32_e32 v237, v50, v236
	v_mul_f32_e32 v236, v51, v239
	v_mul_f32_e32 v239, v55, v239
	v_fma_f32 v236, v55, v238, -v236
	v_fmac_f32_e32 v239, v51, v238
	v_mul_f32_e32 v238, v52, v233
	v_mul_f32_e32 v13, v56, v233
	v_fma_f32 v238, v56, v232, -v238
	v_fmac_f32_e32 v13, v52, v232
	v_mul_f32_e32 v232, v53, v235
	v_fma_f32 v233, v57, v234, -v232
	v_mul_f32_e32 v235, v57, v235
	v_fmac_f32_e32 v235, v53, v234
	v_cvt_pk_bf16_f32 v232, v12, v236
	v_cvt_pk_bf16_f32 v233, v238, v233
	v_cvt_pk_bf16_f32 v234, v237, v239
	v_cvt_pk_bf16_f32 v235, v13, v235
	global_store_dwordx2 v[16:17], v[232:233], off
	global_store_dwordx2 v[16:17], v[234:235], off offset:32
	v_or_b32_e32 v12, s25, v174
	v_ashrrev_i32_e32 v13, 31, v12
	v_lshlrev_b64 v[14:15], 10, v[12:13]
	s_mov_b64 s[36:37], -1
	s_and_b64 vcc, exec, s[10:11]
	v_lshl_add_u64 v[14:15], s[14:15], 0, v[14:15]
	s_cbranch_vccnz .LBB0_2433
	v_mov_b32_e32 v16, v10
	v_mov_b32_e32 v17, v151
	v_lshl_add_u64 v[16:17], v[16:17], 1, v[14:15]
	v_lshl_add_u64 v[16:17], v[16:17], 0, s[20:21]
	s_mov_b64 s[36:37], 0

.LBB0_2435:
	v_mul_f32_e32 v50, v42, v245
	v_fma_f32 v50, v46, v244, -v50
	v_mul_f32_e32 v46, v46, v245
	v_fmac_f32_e32 v46, v42, v244
	v_mul_f32_e32 v42, v43, v247
	v_fma_f32 v42, v47, v246, -v42
	v_mul_f32_e32 v47, v47, v247
	v_fmac_f32_e32 v47, v43, v246
	v_mul_f32_e32 v43, v44, v241
	v_fma_f32 v43, v48, v240, -v43
	v_mul_f32_e32 v48, v48, v241
	v_fmac_f32_e32 v48, v44, v240
	v_mul_f32_e32 v44, v45, v243
	v_fma_f32 v44, v49, v242, -v44
	v_mul_f32_e32 v49, v49, v243
	v_cvt_pk_bf16_f32 v42, v50, v42
	v_cvt_pk_bf16_f32 v43, v43, v44
	s_and_b64 vcc, exec, s[12:13]
	s_mov_b64 s[36:37], -1
	v_fmac_f32_e32 v49, v45, v242
	v_cvt_pk_bf16_f32 v44, v46, v47
	v_cvt_pk_bf16_f32 v45, v48, v49
	global_store_dwordx2 v[16:17], v[42:43], off
	global_store_dwordx2 v[16:17], v[44:45], off offset:32
	s_cbranch_vccnz .LBB0_2437
	v_lshl_add_u64 v[14:15], v[150:151], 1, v[14:15]
	v_lshl_add_u64 v[16:17], v[14:15], 0, s[22:23]
	s_mov_b64 s[36:37], 0

.LBB0_2439:
	v_mul_f32_e32 v12, v34, v245
	v_mul_f32_e32 v245, v38, v245
	v_fma_f32 v12, v38, v244, -v12
	v_fmac_f32_e32 v245, v34, v244
	v_mul_f32_e32 v244, v35, v247
	v_mul_f32_e32 v247, v39, v247
	v_fma_f32 v244, v39, v246, -v244
	v_fmac_f32_e32 v247, v35, v246
	v_mul_f32_e32 v246, v36, v241
	v_mul_f32_e32 v13, v40, v241
	v_fma_f32 v246, v40, v240, -v246
	v_fmac_f32_e32 v13, v36, v240
	v_mul_f32_e32 v240, v37, v243
	v_fma_f32 v241, v41, v242, -v240
	v_mul_f32_e32 v243, v41, v243
	v_fmac_f32_e32 v243, v37, v242
	v_cvt_pk_bf16_f32 v240, v12, v244
	v_cvt_pk_bf16_f32 v241, v246, v241
	v_cvt_pk_bf16_f32 v242, v245, v247
	v_cvt_pk_bf16_f32 v243, v13, v243
	global_store_dwordx2 v[16:17], v[240:241], off
	global_store_dwordx2 v[16:17], v[242:243], off offset:32
	v_or_b32_e32 v12, s25, v175
	v_cmp_gt_i32_e32 vcc, s60, v12
	v_mov_b32_e32 v7, 0
	v_mov_b32_e32 v6, 1.0
	v_mov_b32_e32 v8, 1.0
	v_mov_b32_e32 v9, 0
	v_mov_b32_e32 v2, 1.0
	v_mov_b32_e32 v3, 0
	v_mov_b32_e32 v4, 1.0
	v_mov_b32_e32 v5, 0
	s_and_saveexec_b64 s[36:37], vcc
	s_cbranch_execz .LBB0_2441
	s_bfe_u32 s25, s25, 0x50006
	v_mov_b32_e32 v2, s25
	v_cndmask_b32_e64 v2, v175, v2, s[6:7]
	v_lshlrev_b32_e32 v2, 8, v2
	v_mov_b32_e32 v3, v151
	v_lshl_add_u64 v[2:3], v[154:155], 0, v[2:3]
	global_load_dwordx4 v[6:9], v[2:3], off offset:16
	s_nop 0
	global_load_dwordx4 v[2:5], v[2:3], off
